# speedup vs baseline: 1.0110x; 1.0110x over previous
; __device__ __forceinline__ void dil_attn_phase(const P& p_, int g, char* smem, bool dry = false) {
;     ...
; #pragma unroll
;     for (int et = 0; et < 2; ++et)
; #pragma unroll
;       for (int rg = 0; rg < 4; ++rg) {
;         int e0 = et * 32 + 8 * rg + 4 * hi;
;         h16* dst = O + (size_t)tok * 1024 + h * 64 + e0;
;         h4 ov;
;         if (g > 0) {
;           h4 pv = *(const h4*)dst;
; #pragma unroll
;           for (int i = 0; i < 4; ++i) ov[i] = (h16)((float)pv[i] * wp + o[et][rg * 4 + i] * wc);
;         } else {
; #pragma unroll
;           for (int i = 0; i < 4; ++i) ov[i] = (h16)(o[et][rg * 4 + i] * wc);
;         }
;         *(h4*)dst = ov;
.LBB0_953:
	v_lshlrev_b64 v[6:7], 11, v[80:81]
	v_lshl_add_u64 v[6:7], s[40:41], 0, v[6:7]
	s_lshl_b32 s88, s27, 1
	v_lshl_add_u64 v[6:7], v[6:7], 0, s[88:89]
	v_mov_b32_e32 v67, v1
	v_lshl_add_u64 v[6:7], v[6:7], 0, v[66:67]
	s_and_b64 vcc, exec, s[48:49]
	s_cbranch_vccz .LBB0_979
	global_load_dwordx2 v[188:189], v[6:7], off
	global_load_dwordx2 v[190:191], v[6:7], off offset:16
	global_load_dwordx2 v[192:193], v[6:7], off offset:32
	global_load_dwordx2 v[194:195], v[6:7], off offset:48
	global_load_dwordx2 v[196:197], v[6:7], off offset:64
	global_load_dwordx2 v[198:199], v[6:7], off offset:80
	global_load_dwordx2 v[200:201], v[6:7], off offset:96
	global_load_dwordx2 v[202:203], v[6:7], off offset:112
	s_waitcnt vmcnt(0)
	v_mov_b32_e32 v8, v188
	v_mov_b32_e32 v9, v189
	v_cvt_f32_f16_sdwa v13, v8 dst_sel:DWORD dst_unused:UNUSED_PAD src0_sel:WORD_1
	v_cvt_f32_f16_e32 v12, v8
	v_pk_mul_f32 v[12:13], v[4:5], v[12:13] op_sel_hi:[0,1]
	v_pk_fma_f32 v[12:13], v[110:111], v[4:5], v[12:13] op_sel:[0,1,0]
	s_nop 0
	v_cvt_pk_f16_f32 v8, v12, v13
	v_cvt_f32_f16_e32 v12, v9
	v_mov_b32_e32 v13, v108
	v_pk_mul_f32 v[12:13], v[4:5], v[12:13]
	s_nop 0
	v_add_f32_e32 v3, v13, v12
	v_cvt_f32_f16_sdwa v12, v9 dst_sel:DWORD dst_unused:UNUSED_PAD src0_sel:WORD_1
	v_cvt_f16_f32_e32 v3, v3
	v_mov_b32_e32 v13, v109
	v_pk_mul_f32 v[12:13], v[4:5], v[12:13]
	v_pack_b32_f16 v3, v3, 0
	v_add_f32_e32 v9, v13, v12
	s_mov_b32 s2, 0x5040100
	s_cbranch_execnz .LBB0_956

; __device__ __forceinline__ void dil_attn_phase(const P& p_, int g, char* smem, bool dry = false) {
;     ...
;         if (g > 0) {
;           h4 pv = *(const h4*)dst;
; #pragma unroll
;           for (int i = 0; i < 4; ++i) ov[i] = (h16)((float)pv[i] * wp + o[et][rg * 4 + i] * wc);
;         } else {
; #pragma unroll
;           for (int i = 0; i < 4; ++i) ov[i] = (h16)(o[et][rg * 4 + i] * wc);
;         }
;         *(h4*)dst = ov;
.LBB0_956:
	v_cvt_f16_f32_e32 v9, v9
	s_and_b64 vcc, exec, s[48:49]
	v_perm_b32 v9, v9, v3, s2
	global_store_dwordx2 v[6:7], v[8:9], off
	s_cbranch_vccz .LBB0_980
	v_mov_b32_e32 v8, v190
	v_mov_b32_e32 v9, v191
	v_cvt_f32_f16_sdwa v13, v8 dst_sel:DWORD dst_unused:UNUSED_PAD src0_sel:WORD_1
	v_cvt_f32_f16_e32 v12, v8
	v_pk_mul_f32 v[12:13], v[4:5], v[12:13] op_sel_hi:[0,1]
	v_pk_fma_f32 v[12:13], v[98:99], v[4:5], v[12:13] op_sel:[0,1,0]
	s_nop 0
	v_cvt_pk_f16_f32 v8, v12, v13
	v_cvt_f32_f16_e32 v12, v9
	v_mov_b32_e32 v13, v96
	v_pk_mul_f32 v[12:13], v[4:5], v[12:13]
	s_nop 0
	v_add_f32_e32 v3, v13, v12
	v_cvt_f32_f16_sdwa v12, v9 dst_sel:DWORD dst_unused:UNUSED_PAD src0_sel:WORD_1
	v_cvt_f16_f32_e32 v3, v3
	v_mov_b32_e32 v13, v97
	v_pk_mul_f32 v[12:13], v[4:5], v[12:13]
	v_pack_b32_f16 v3, v3, 0
	v_add_f32_e32 v9, v13, v12
	s_cbranch_execnz .LBB0_959

; __device__ __forceinline__ void dil_attn_phase(const P& p_, int g, char* smem, bool dry = false) {
;     ...
;         if (g > 0) {
;           h4 pv = *(const h4*)dst;
; #pragma unroll
;           for (int i = 0; i < 4; ++i) ov[i] = (h16)((float)pv[i] * wp + o[et][rg * 4 + i] * wc);
;         } else {
; #pragma unroll
;           for (int i = 0; i < 4; ++i) ov[i] = (h16)(o[et][rg * 4 + i] * wc);
;         }
;         *(h4*)dst = ov;
.LBB0_959:
	v_cvt_f16_f32_e32 v9, v9
	s_and_b64 vcc, exec, s[48:49]
	v_perm_b32 v9, v9, v3, s2
	global_store_dwordx2 v[6:7], v[8:9], off offset:16
	s_cbranch_vccz .LBB0_981
	v_mov_b32_e32 v8, v192
	v_mov_b32_e32 v9, v193
	v_cvt_f32_f16_sdwa v13, v8 dst_sel:DWORD dst_unused:UNUSED_PAD src0_sel:WORD_1
	v_cvt_f32_f16_e32 v12, v8
	v_pk_mul_f32 v[12:13], v[4:5], v[12:13] op_sel_hi:[0,1]
	v_pk_fma_f32 v[12:13], v[92:93], v[4:5], v[12:13] op_sel:[0,1,0]
	s_nop 0
	v_cvt_pk_f16_f32 v8, v12, v13
	v_cvt_f32_f16_e32 v12, v9
	v_mov_b32_e32 v13, v90
	v_pk_mul_f32 v[12:13], v[4:5], v[12:13]
	s_nop 0
	v_add_f32_e32 v3, v13, v12
	v_cvt_f32_f16_sdwa v12, v9 dst_sel:DWORD dst_unused:UNUSED_PAD src0_sel:WORD_1
	v_cvt_f16_f32_e32 v3, v3
	v_mov_b32_e32 v13, v91
	v_pk_mul_f32 v[12:13], v[4:5], v[12:13]
	v_pack_b32_f16 v3, v3, 0
	v_add_f32_e32 v9, v13, v12
	s_cbranch_execnz .LBB0_962

; __device__ __forceinline__ void dil_attn_phase(const P& p_, int g, char* smem, bool dry = false) {
;     ...
;         if (g > 0) {
;           h4 pv = *(const h4*)dst;
; #pragma unroll
;           for (int i = 0; i < 4; ++i) ov[i] = (h16)((float)pv[i] * wp + o[et][rg * 4 + i] * wc);
;         } else {
; #pragma unroll
;           for (int i = 0; i < 4; ++i) ov[i] = (h16)(o[et][rg * 4 + i] * wc);
;         }
;         *(h4*)dst = ov;
.LBB0_962:
	v_cvt_f16_f32_e32 v9, v9
	s_and_b64 vcc, exec, s[48:49]
	v_perm_b32 v9, v9, v3, s2
	global_store_dwordx2 v[6:7], v[8:9], off offset:32
	s_cbranch_vccz .LBB0_982
	v_mov_b32_e32 v8, v194
	v_mov_b32_e32 v9, v195
	v_cvt_f32_f16_sdwa v13, v8 dst_sel:DWORD dst_unused:UNUSED_PAD src0_sel:WORD_1
	v_cvt_f32_f16_e32 v12, v8
	v_pk_mul_f32 v[12:13], v[4:5], v[12:13] op_sel_hi:[0,1]
	v_pk_fma_f32 v[12:13], v[88:89], v[4:5], v[12:13] op_sel:[0,1,0]
	s_nop 0
	v_cvt_pk_f16_f32 v8, v12, v13
	v_cvt_f32_f16_e32 v12, v9
	v_mov_b32_e32 v13, v86
	v_pk_mul_f32 v[12:13], v[4:5], v[12:13]
	s_nop 0
	v_add_f32_e32 v3, v13, v12
	v_cvt_f32_f16_sdwa v12, v9 dst_sel:DWORD dst_unused:UNUSED_PAD src0_sel:WORD_1
	v_cvt_f16_f32_e32 v3, v3
	v_mov_b32_e32 v13, v87
	v_pk_mul_f32 v[12:13], v[4:5], v[12:13]
	v_pack_b32_f16 v3, v3, 0
	v_add_f32_e32 v9, v13, v12
	s_cbranch_execnz .LBB0_965

; __device__ __forceinline__ void dil_attn_phase(const P& p_, int g, char* smem, bool dry = false) {
;     ...
;         if (g > 0) {
;           h4 pv = *(const h4*)dst;
; #pragma unroll
;           for (int i = 0; i < 4; ++i) ov[i] = (h16)((float)pv[i] * wp + o[et][rg * 4 + i] * wc);
;         } else {
; #pragma unroll
;           for (int i = 0; i < 4; ++i) ov[i] = (h16)(o[et][rg * 4 + i] * wc);
;         }
;         *(h4*)dst = ov;
.LBB0_965:
	v_cvt_f16_f32_e32 v9, v9
	s_and_b64 vcc, exec, s[48:49]
	v_perm_b32 v9, v9, v3, s2
	global_store_dwordx2 v[6:7], v[8:9], off offset:48
	s_cbranch_vccz .LBB0_983
	v_mov_b32_e32 v14, v82
	v_mov_b32_e32 v15, v4
	v_mov_b32_e32 v8, v196
	v_mov_b32_e32 v9, v197
	v_cvt_f32_f16_sdwa v13, v8 dst_sel:DWORD dst_unused:UNUSED_PAD src0_sel:WORD_1
	v_cvt_f32_f16_e32 v12, v8
	v_pk_mul_f32 v[12:13], v[4:5], v[12:13] op_sel_hi:[0,1]
	v_pk_fma_f32 v[12:13], v[84:85], v[4:5], v[12:13] op_sel:[0,1,0]
	s_nop 0
	v_cvt_pk_f16_f32 v8, v12, v13
	v_cvt_f32_f16_e32 v13, v9
	v_mov_b32_e32 v12, v5
	v_pk_mul_f32 v[12:13], v[14:15], v[12:13]
	s_nop 0
	v_add_f32_e32 v3, v12, v13
	v_cvt_f32_f16_sdwa v13, v9 dst_sel:DWORD dst_unused:UNUSED_PAD src0_sel:WORD_1
	v_cvt_f16_f32_e32 v3, v3
	v_pk_mov_b32 v[14:15], v[82:83], v[4:5] op_sel:[1,0]
	v_mov_b32_e32 v12, v5
	v_pk_mul_f32 v[12:13], v[14:15], v[12:13]
	v_pack_b32_f16 v3, v3, 0
	v_add_f32_e32 v9, v12, v13
	s_cbranch_execnz .LBB0_968

; __device__ __forceinline__ void dil_attn_phase(const P& p_, int g, char* smem, bool dry = false) {
;     ...
;         if (g > 0) {
;           h4 pv = *(const h4*)dst;
; #pragma unroll
;           for (int i = 0; i < 4; ++i) ov[i] = (h16)((float)pv[i] * wp + o[et][rg * 4 + i] * wc);
;         } else {
; #pragma unroll
;           for (int i = 0; i < 4; ++i) ov[i] = (h16)(o[et][rg * 4 + i] * wc);
;         }
;         *(h4*)dst = ov;
.LBB0_968:
	v_cvt_f16_f32_e32 v9, v9
	s_and_b64 vcc, exec, s[48:49]
	v_perm_b32 v9, v9, v3, s2
	global_store_dwordx2 v[6:7], v[8:9], off offset:64
	s_cbranch_vccz .LBB0_984
	v_mov_b32_e32 v14, v76
	v_mov_b32_e32 v15, v4
	v_mov_b32_e32 v8, v198
	v_mov_b32_e32 v9, v199
	v_cvt_f32_f16_sdwa v13, v8 dst_sel:DWORD dst_unused:UNUSED_PAD src0_sel:WORD_1
	v_cvt_f32_f16_e32 v12, v8
	v_pk_mul_f32 v[12:13], v[4:5], v[12:13] op_sel_hi:[0,1]
	v_pk_fma_f32 v[12:13], v[78:79], v[4:5], v[12:13] op_sel:[0,1,0]
	s_nop 0
	v_cvt_pk_f16_f32 v8, v12, v13
	v_cvt_f32_f16_e32 v13, v9
	v_mov_b32_e32 v12, v5
	v_pk_mul_f32 v[12:13], v[14:15], v[12:13]
	s_nop 0
	v_add_f32_e32 v3, v12, v13
	v_cvt_f32_f16_sdwa v13, v9 dst_sel:DWORD dst_unused:UNUSED_PAD src0_sel:WORD_1
	v_cvt_f16_f32_e32 v3, v3
	v_pk_mov_b32 v[14:15], v[76:77], v[4:5] op_sel:[1,0]
	v_mov_b32_e32 v12, v5
	v_pk_mul_f32 v[12:13], v[14:15], v[12:13]
	v_pack_b32_f16 v3, v3, 0
	v_add_f32_e32 v9, v12, v13
	s_cbranch_execnz .LBB0_971

; __device__ __forceinline__ void dil_attn_phase(const P& p_, int g, char* smem, bool dry = false) {
;     ...
;         if (g > 0) {
;           h4 pv = *(const h4*)dst;
; #pragma unroll
;           for (int i = 0; i < 4; ++i) ov[i] = (h16)((float)pv[i] * wp + o[et][rg * 4 + i] * wc);
;         } else {
; #pragma unroll
;           for (int i = 0; i < 4; ++i) ov[i] = (h16)(o[et][rg * 4 + i] * wc);
;         }
;         *(h4*)dst = ov;
.LBB0_971:
	v_cvt_f16_f32_e32 v9, v9
	s_and_b64 vcc, exec, s[48:49]
	v_perm_b32 v9, v9, v3, s2
	global_store_dwordx2 v[6:7], v[8:9], off offset:80
	s_cbranch_vccz .LBB0_985
	v_mov_b32_e32 v14, v72
	v_mov_b32_e32 v15, v4
	v_mov_b32_e32 v8, v200
	v_mov_b32_e32 v9, v201
	v_cvt_f32_f16_sdwa v13, v8 dst_sel:DWORD dst_unused:UNUSED_PAD src0_sel:WORD_1
	v_cvt_f32_f16_e32 v12, v8
	v_pk_mul_f32 v[12:13], v[4:5], v[12:13] op_sel_hi:[0,1]
	v_pk_fma_f32 v[12:13], v[74:75], v[4:5], v[12:13] op_sel:[0,1,0]
	s_nop 0
	v_cvt_pk_f16_f32 v8, v12, v13
	v_cvt_f32_f16_e32 v13, v9
	v_mov_b32_e32 v12, v5
	v_pk_mul_f32 v[12:13], v[14:15], v[12:13]
	s_nop 0
	v_add_f32_e32 v3, v12, v13
	v_cvt_f32_f16_sdwa v13, v9 dst_sel:DWORD dst_unused:UNUSED_PAD src0_sel:WORD_1
	v_cvt_f16_f32_e32 v3, v3
	v_pk_mov_b32 v[14:15], v[72:73], v[4:5] op_sel:[1,0]
	v_mov_b32_e32 v12, v5
	v_pk_mul_f32 v[12:13], v[14:15], v[12:13]
	v_pack_b32_f16 v3, v3, 0
	v_add_f32_e32 v9, v12, v13
	s_cbranch_execnz .LBB0_974

; __device__ __forceinline__ void dil_attn_phase(const P& p_, int g, char* smem, bool dry = false) {
;     ...
;         if (g > 0) {
;           h4 pv = *(const h4*)dst;
; #pragma unroll
;           for (int i = 0; i < 4; ++i) ov[i] = (h16)((float)pv[i] * wp + o[et][rg * 4 + i] * wc);
;         } else {
; #pragma unroll
;           for (int i = 0; i < 4; ++i) ov[i] = (h16)(o[et][rg * 4 + i] * wc);
;         }
;         *(h4*)dst = ov;
.LBB0_974:
	v_cvt_f16_f32_e32 v9, v9
	s_and_b64 vcc, exec, s[48:49]
	v_perm_b32 v9, v9, v3, s2
	global_store_dwordx2 v[6:7], v[8:9], off offset:96
	s_cbranch_vccz .LBB0_986
	v_mov_b32_e32 v14, v68
	v_mov_b32_e32 v15, v4
	v_mov_b32_e32 v8, v202
	v_mov_b32_e32 v9, v203
	v_cvt_f32_f16_sdwa v13, v8 dst_sel:DWORD dst_unused:UNUSED_PAD src0_sel:WORD_1
	v_cvt_f32_f16_e32 v12, v8
	v_pk_mul_f32 v[12:13], v[4:5], v[12:13] op_sel_hi:[0,1]
	v_pk_fma_f32 v[12:13], v[70:71], v[4:5], v[12:13] op_sel:[0,1,0]
	s_nop 0
	v_cvt_pk_f16_f32 v8, v12, v13
	v_cvt_f32_f16_e32 v13, v9
	v_mov_b32_e32 v12, v5
	v_pk_mul_f32 v[12:13], v[14:15], v[12:13]
	s_nop 0
	v_add_f32_e32 v3, v12, v13
	v_cvt_f32_f16_sdwa v12, v9 dst_sel:DWORD dst_unused:UNUSED_PAD src0_sel:WORD_1
	v_cvt_f16_f32_e32 v3, v3
	v_mov_b32_e32 v13, v69
	v_pk_mul_f32 v[12:13], v[12:13], v[4:5]
	v_pack_b32_f16 v3, v3, 0
	v_add_f32_e32 v9, v13, v12
	s_cbranch_execnz .LBB0_977
